# MIX lists: the std-prompt attention items move from the two-std-sample attention blocks to the sample-chain partner blocks (86 us vs 64 us estimated lists)
# baseline (speedup 1.0000x reference)
.Lms_y:
	s_cmpk_lt_u32 s0, 0x180
	s_cbranch_scc0 .Lms_y2
	s_movk_i32 s2, 424
	s_cmpk_eq_u32 s1, 128
	s_cbranch_scc1 .Lms_set
	s_movk_i32 s2, 552
	s_cmpk_eq_u32 s1, 424
	s_cbranch_scc1 .Lms_set
	s_movk_i32 s2, 680
	s_cmpk_eq_u32 s1, 552
	s_cbranch_scc1 .Lms_set
	s_branch .LBB0_1139
.Lms_y2:
	s_movk_i32 s2, 680
	s_cmpk_eq_u32 s1, 128
	s_cbranch_scc1 .Lms_set
	s_movk_i32 s2, 936
	s_cmpk_eq_u32 s1, 680
	s_cbranch_scc1 .Lms_set
	s_movk_i32 s2, 808
	s_cmpk_eq_u32 s1, 936
	s_cbranch_scc1 .Lms_set
	s_cmpk_eq_u32 s1, 808
	s_cbranch_scc0 .LBB0_1139
	s_movk_i32 s2, 256
	s_cmpk_lt_u32 s0, 0x1a8
	s_cbranch_scc0 .LBB0_1139
